# L1 K-norm+rope phase: gain loads hoisted, rope loads batched, branch-free element code
# speedup vs baseline: 1.0039x; 1.0039x over previous
; #define OPAQUE_IDS int tx = threadIdx.x; int bx = blockIdx.x; asm volatile("" : "+v"(tx), "+s"(bx));
; template <int HS>
; DI void qknorm_phase(bf16_t* QK, int RL, const float* kgain, int gain_mod, const f32x2* rope) {
;     OPAQUE_IDS
;     const int lane = tx & 63, gw = bx * 8 + (tx >> 6), nw = gridDim.x * 8;
;     const int lpr = (RL - 1024) / HS, rpw = 64 / lpr, rsub = lane / lpr, kl = lane - rsub * lpr, seg = kl >> 1, half = kl & 1;
;     const float* gn = kgain + (gain_mod ? (seg % gain_mod) * 2 * HS : 0) + half * HS;
;     for (int row0 = gw * rpw; row0 < T; row0 += nw * rpw) {
;         const int row = row0 + rsub; const bool act = row < T; const int rowc = act ? row : T - 1;
;         const int b = rowc / LT, pos = rowc - b * LT;
;         float x[HS]; float ss = 0.f;
;         bf16_t* ptr = QK + (size_t)rowc * RL + 1024 + kl * HS;
.LBB0_1162:
	s_or_b64 exec, exec, s[0:1]
	s_mov_b32 s0, s87
	v_mov_b32_e32 v4, v252
	s_waitcnt lgkmcnt(0)
	s_barrier
	s_add_u32 s10, s68, 0x8d8000
	v_ashrrev_i32_e32 v0, 5, v4
	v_and_b32_e32 v0, -2, v0
	v_lshl_add_u32 v20, s0, 4, v0
	s_movk_i32 s7, 0x4800
	s_addc_u32 s11, s69, 0
	v_cmp_gt_i32_e32 vcc, s7, v20
	s_and_saveexec_b64 s[12:13], vcc
	s_cbranch_execz .LBB0_1231
	v_lshlrev_b32_e32 v0, 7, v4
	v_readlane_b32 s36, v254, 7
	v_and_b32_e32 v5, 1, v4
	v_and_b32_e32 v0, 0x100, v0
	v_mov_b32_e32 v1, 0
	v_readlane_b32 s46, v254, 17
	v_readlane_b32 s47, v254, 18
	v_bfe_u32 v21, v4, 5, 1
	v_cmp_eq_u32_e32 vcc, 0, v5
	v_lshl_add_u64 v[2:3], s[46:47], 0, v[0:1]
	v_lshlrev_b32_e32 v0, 7, v5
	v_lshl_add_u64 v[2:3], v[2:3], 0, v[0:1]
	v_lshlrev_b32_e32 v0, 6, v4
	v_and_b32_e32 v0, 0x7c0, v0
	s_lshl_b32 s14, s26, 4
	v_lshl_add_u64 v[4:5], s[96:97], 0, v[0:1]
	s_mov_b64 s[30:31], 0
	s_movk_i32 s15, 0x47ff
	v_mov_b32_e32 v22, 0x47ff
	s_mov_b32 s34, 0x38e38e39
	v_mov_b32_e32 v23, 0x358637bd
	s_mov_b32 s35, 0x800000
	s_movk_i32 s36, 0xff
	v_readlane_b32 s37, v254, 8
	v_readlane_b32 s38, v254, 9
	v_readlane_b32 s39, v254, 10
	v_readlane_b32 s40, v254, 11
	v_readlane_b32 s41, v254, 12
	v_readlane_b32 s42, v254, 13
	v_readlane_b32 s43, v254, 14
	v_readlane_b32 s44, v254, 15
	v_readlane_b32 s45, v254, 16
	v_readlane_b32 s48, v254, 19
	v_readlane_b32 s49, v254, 20
	v_readlane_b32 s50, v254, 21
	v_readlane_b32 s51, v254, 22
	global_load_dwordx4 v[80:83], v[2:3], off
	global_load_dwordx4 v[84:87], v[2:3], off offset:16
	global_load_dwordx4 v[88:91], v[2:3], off offset:32
	global_load_dwordx4 v[92:95], v[2:3], off offset:48
	global_load_dwordx4 v[96:99], v[2:3], off offset:64
	global_load_dwordx4 v[100:103], v[2:3], off offset:80
	global_load_dwordx4 v[104:107], v[2:3], off offset:96
	global_load_dwordx4 v[108:111], v[2:3], off offset:112
	s_branch .LBB0_1165

; DI float bflo(unsigned w) { return __uint_as_float(w << 16); }
; DI float bfhi(unsigned w) { return __uint_as_float(w & 0xffff0000u); }
; template <int CTRL> DI float dpp_f(float x) { return __int_as_float(__builtin_amdgcn_update_dpp(0, __float_as_int(x), CTRL, 0xF, 0xF, true)); }
; template <int HS>
; DI void qknorm_phase(bf16_t* QK, int RL, const float* kgain, int gain_mod, const f32x2* rope) {
;     ...
;     for (int row0 = gw * rpw; row0 < T; row0 += nw * rpw) {
;         const int row = row0 + rsub; const bool act = row < T; const int rowc = act ? row : T - 1;
;         const int b = rowc / LT, pos = rowc - b * LT;
;         float x[HS]; float ss = 0.f;
;         bf16_t* ptr = QK + (size_t)rowc * RL + 1024 + kl * HS;
; #pragma unroll
;         for (int c = 0; c < HS / 8; ++c) { const u32x4 w = *(const u32x4*)(ptr + c * 8);
;             x[c * 8 + 0] = bflo(w.x); x[c * 8 + 1] = bfhi(w.x); x[c * 8 + 2] = bflo(w.y); x[c * 8 + 3] = bfhi(w.y);
;             x[c * 8 + 4] = bflo(w.z); x[c * 8 + 5] = bfhi(w.z); x[c * 8 + 6] = bflo(w.w); x[c * 8 + 7] = bfhi(w.w); }
; #pragma unroll
;         for (int e = 0; e < HS; ++e) ss += x[e] * x[e];
;         ss += dpp_f<0xB1>(ss);
;         const float r = rsqrtf(ss * (1.f / (2 * HS)) + EPS);
;         const bool lat = pos >= LC; const f32x2* rp = rope + (size_t)(lat ? pos - LC : 0) * HS;
; #pragma unroll
;         for (int e = 0; e < HS; ++e) {
;             float v = x[e] * r * gn[e];
.LBB0_1165:
	v_add_u32_e32 v0, v21, v20
	v_cmp_gt_i32_e64 s[2:3], s7, v0
	s_nop 1
	v_cndmask_b32_e64 v24, v22, v0, s[2:3]
	v_ashrrev_i32_e32 v25, 31, v24
	v_lshlrev_b64 v[6:7], 12, v[24:25]
	v_lshl_add_u64 v[6:7], v[4:5], 0, v[6:7]
	global_load_dwordx4 v[8:11], v[6:7], off offset:2048
	global_load_dwordx4 v[12:15], v[6:7], off offset:2064
	global_load_dwordx4 v[16:19], v[6:7], off offset:2080
	global_load_dwordx4 v[46:49], v[6:7], off offset:2096
	v_mul_hi_i32 v0, v24, s34
	v_lshrrev_b32_e32 v25, 31, v0
	v_ashrrev_i32_e32 v0, 9, v0
	v_add_u32_e32 v0, v0, v25
	v_mul_i32_i24_e32 v0, 0x900, v0
	v_sub_u32_e32 v0, v24, v0
	v_cmp_lt_i32_e64 s[0:1], s36, v0
	v_max_i32_e32 v0, 0x100, v0
	v_add_u32_e32 v0, 0xffffff00, v0
	v_lshlrev_b64 v[56:57], 8, v[0:1]
	v_lshl_add_u64 v[56:57], s[10:11], 0, v[56:57]
	global_load_dwordx4 v[144:147], v[56:57], off
	global_load_dwordx4 v[148:151], v[56:57], off offset:16
	global_load_dwordx4 v[152:155], v[56:57], off offset:32
	global_load_dwordx4 v[156:159], v[56:57], off offset:48
	global_load_dwordx4 v[160:163], v[56:57], off offset:64
	global_load_dwordx4 v[164:167], v[56:57], off offset:80
	global_load_dwordx4 v[168:171], v[56:57], off offset:96
	global_load_dwordx4 v[172:175], v[56:57], off offset:112
	global_load_dwordx4 v[176:179], v[56:57], off offset:128
	global_load_dwordx4 v[180:183], v[56:57], off offset:144
	global_load_dwordx4 v[184:187], v[56:57], off offset:160
	global_load_dwordx4 v[188:191], v[56:57], off offset:176
	global_load_dwordx4 v[192:195], v[56:57], off offset:192
	global_load_dwordx4 v[196:199], v[56:57], off offset:208
	global_load_dwordx4 v[200:203], v[56:57], off offset:224
	global_load_dwordx4 v[204:207], v[56:57], off offset:240
	s_waitcnt vmcnt(19)
	v_and_b32_e32 v25, 0xffff0000, v8
	v_lshlrev_b32_e32 v55, 16, v8
	v_mul_f32_e32 v24, v25, v25
	v_lshlrev_b32_e32 v26, 16, v9
	v_fmac_f32_e32 v24, v55, v55
	v_and_b32_e32 v27, 0xffff0000, v9
	v_fmac_f32_e32 v24, v26, v26
	v_lshlrev_b32_e32 v28, 16, v10
	v_fmac_f32_e32 v24, v27, v27
	v_and_b32_e32 v29, 0xffff0000, v10
	v_fmac_f32_e32 v24, v28, v28
	v_lshlrev_b32_e32 v30, 16, v11
	v_fmac_f32_e32 v24, v29, v29
	v_and_b32_e32 v31, 0xffff0000, v11
	v_fmac_f32_e32 v24, v30, v30
	s_waitcnt vmcnt(18)
	v_lshlrev_b32_e32 v32, 16, v12
	v_fmac_f32_e32 v24, v31, v31
	v_and_b32_e32 v34, 0xffff0000, v12
	v_fmac_f32_e32 v24, v32, v32
	v_lshlrev_b32_e32 v36, 16, v13
	v_fmac_f32_e32 v24, v34, v34
	v_and_b32_e32 v38, 0xffff0000, v13
	v_fmac_f32_e32 v24, v36, v36
	v_lshlrev_b32_e32 v40, 16, v14
	v_fmac_f32_e32 v24, v38, v38
	v_and_b32_e32 v42, 0xffff0000, v14
	v_fmac_f32_e32 v24, v40, v40
	v_lshlrev_b32_e32 v44, 16, v15
	v_fmac_f32_e32 v24, v42, v42
	v_and_b32_e32 v45, 0xffff0000, v15
	v_fmac_f32_e32 v24, v44, v44
	s_waitcnt vmcnt(17)
	v_lshlrev_b32_e32 v43, 16, v16
	v_fmac_f32_e32 v24, v45, v45
	v_and_b32_e32 v41, 0xffff0000, v16
	v_fmac_f32_e32 v24, v43, v43
	v_lshlrev_b32_e32 v39, 16, v17
	v_fmac_f32_e32 v24, v41, v41
	v_and_b32_e32 v37, 0xffff0000, v17
	v_fmac_f32_e32 v24, v39, v39
	v_lshlrev_b32_e32 v35, 16, v18
	v_fmac_f32_e32 v24, v37, v37
	v_and_b32_e32 v33, 0xffff0000, v18
	v_and_b32_e32 v18, 0xffff0000, v19
	v_lshlrev_b32_e32 v19, 16, v19
	v_fmac_f32_e32 v24, v35, v35
	v_pk_mul_f32 v[10:11], v[18:19], v[18:19]
	v_fmac_f32_e32 v24, v33, v33
	s_waitcnt vmcnt(16)
	v_and_b32_e32 v16, 0xffff0000, v46
	v_lshlrev_b32_e32 v17, 16, v46
	v_add_f32_e32 v11, v11, v24
	v_and_b32_e32 v14, 0xffff0000, v47
	v_lshlrev_b32_e32 v15, 16, v47
	v_pk_mul_f32 v[46:47], v[16:17], v[16:17]
	v_add_f32_e32 v10, v10, v11
	v_add_f32_e32 v10, v47, v10
	v_and_b32_e32 v12, 0xffff0000, v48
	v_lshlrev_b32_e32 v13, 16, v48
	v_and_b32_e32 v8, 0xffff0000, v49
	v_lshlrev_b32_e32 v9, 16, v49
	v_pk_mul_f32 v[48:49], v[14:15], v[14:15]
	v_add_f32_e32 v10, v46, v10
	v_add_f32_e32 v10, v49, v10
	v_pk_mul_f32 v[50:51], v[12:13], v[12:13]
	v_add_f32_e32 v10, v48, v10
	v_add_f32_e32 v10, v51, v10
	v_pk_mul_f32 v[52:53], v[8:9], v[8:9]
	v_add_f32_e32 v10, v50, v10
	v_add_f32_e32 v10, v53, v10
	v_add_f32_e32 v10, v52, v10
	s_nop 1
	v_add_f32_dpp v10, v10, v10 quad_perm:[1,0,3,2] row_mask:0xf bank_mask:0xf bound_ctrl:1
	v_fmamk_f32 v10, v10, 0x3c800000, v23
	v_mul_f32_e32 v11, 0x4b800000, v10
	v_cmp_gt_f32_e64 s[4:5], s35, v10
	s_nop 1
	v_cndmask_b32_e64 v10, v10, v11, s[4:5]
	v_rsq_f32_e32 v24, v10
	v_lshlrev_b64 v[10:11], 8, v[0:1]
	v_lshl_add_u64 v[10:11], s[10:11], 0, v[10:11]
	v_mul_f32_e32 v0, 0x45800000, v24
	v_cndmask_b32_e64 v24, v24, v0, s[4:5]
	v_mul_f32_e32 v0, v24, v55
	v_mul_f32_e32 v25, v24, v25
	v_mul_f32_e32 v26, v24, v26
	v_mul_f32_e32 v27, v24, v27
	v_mul_f32_e32 v28, v24, v28
	v_mul_f32_e32 v29, v24, v29
	v_mul_f32_e32 v30, v24, v30
	v_mul_f32_e32 v31, v24, v31
	v_mul_f32_e32 v32, v24, v32
	v_mul_f32_e32 v34, v24, v34
	v_mul_f32_e32 v36, v24, v36
	v_mul_f32_e32 v38, v24, v38
	v_mul_f32_e32 v40, v24, v40
	v_mul_f32_e32 v42, v24, v42
	v_mul_f32_e32 v44, v24, v44
	v_mul_f32_e32 v45, v24, v45
	v_mul_f32_e32 v43, v24, v43
	v_mul_f32_e32 v41, v24, v41
	v_mul_f32_e32 v39, v24, v39
	v_mul_f32_e32 v37, v24, v37
	v_mul_f32_e32 v35, v24, v35
	v_mul_f32_e32 v33, v24, v33
	v_mul_f32_e32 v19, v24, v19
	v_mul_f32_e32 v18, v24, v18
	v_mul_f32_e32 v17, v24, v17
	v_mul_f32_e32 v16, v24, v16
	v_mul_f32_e32 v15, v24, v15
	v_mul_f32_e32 v14, v24, v14
	v_mul_f32_e32 v13, v24, v13
	v_mul_f32_e32 v12, v24, v12
	v_mul_f32_e32 v9, v24, v9
	v_mul_f32_e32 v8, v24, v8
	v_mul_f32_e32 v0, v0, v80
	v_mul_f32_e32 v25, v25, v81
	v_mul_f32_e32 v26, v26, v82
	v_mul_f32_e32 v27, v27, v83
	v_mul_f32_e32 v28, v28, v84
	v_mul_f32_e32 v29, v29, v85
	v_mul_f32_e32 v30, v30, v86
	v_mul_f32_e32 v31, v31, v87
; template <int CTRL> DI float dpp_f(float x) { return __int_as_float(__builtin_amdgcn_update_dpp(0, __float_as_int(x), CTRL, 0xF, 0xF, true)); }
; template <int HS>
; DI void qknorm_phase(bf16_t* QK, int RL, const float* kgain, int gain_mod, const f32x2* rope) {
;     ...
;         for (int e = 0; e < HS; ++e) {
;             float v = x[e] * r * gn[e];
;             const float o = dpp_f<0xB1>(v);
	v_mul_f32_e32 v32, v32, v88
	v_mul_f32_e32 v34, v34, v89
	v_mul_f32_e32 v36, v36, v90
	v_mul_f32_e32 v38, v38, v91
	v_mul_f32_e32 v40, v40, v92
	v_mul_f32_e32 v42, v42, v93
	v_mul_f32_e32 v44, v44, v94
	v_mul_f32_e32 v45, v45, v95
	v_mul_f32_e32 v43, v43, v96
	v_mul_f32_e32 v41, v41, v97
	v_mul_f32_e32 v39, v39, v98
	v_mul_f32_e32 v37, v37, v99
	v_mul_f32_e32 v35, v35, v100
	v_mul_f32_e32 v33, v33, v101
	v_mul_f32_e32 v19, v19, v102
	v_mul_f32_e32 v18, v18, v103
	v_mul_f32_e32 v17, v17, v104
	v_mul_f32_e32 v16, v16, v105
	v_mul_f32_e32 v15, v15, v106
	v_mul_f32_e32 v14, v14, v107
	v_mul_f32_e32 v13, v13, v108
	v_mul_f32_e32 v12, v12, v109
	v_mul_f32_e32 v9, v9, v110
	v_mul_f32_e32 v8, v8, v111
	v_mov_b32_dpp v208, v0 quad_perm:[1,0,3,2] row_mask:0xf bank_mask:0xf bound_ctrl:1
	v_mov_b32_dpp v209, v25 quad_perm:[1,0,3,2] row_mask:0xf bank_mask:0xf bound_ctrl:1
	v_mov_b32_dpp v210, v26 quad_perm:[1,0,3,2] row_mask:0xf bank_mask:0xf bound_ctrl:1
	v_mov_b32_dpp v211, v27 quad_perm:[1,0,3,2] row_mask:0xf bank_mask:0xf bound_ctrl:1
	v_mov_b32_dpp v212, v28 quad_perm:[1,0,3,2] row_mask:0xf bank_mask:0xf bound_ctrl:1
	v_mov_b32_dpp v213, v29 quad_perm:[1,0,3,2] row_mask:0xf bank_mask:0xf bound_ctrl:1
	v_mov_b32_dpp v214, v30 quad_perm:[1,0,3,2] row_mask:0xf bank_mask:0xf bound_ctrl:1
	v_mov_b32_dpp v215, v31 quad_perm:[1,0,3,2] row_mask:0xf bank_mask:0xf bound_ctrl:1
	v_mov_b32_dpp v216, v32 quad_perm:[1,0,3,2] row_mask:0xf bank_mask:0xf bound_ctrl:1
	v_mov_b32_dpp v217, v34 quad_perm:[1,0,3,2] row_mask:0xf bank_mask:0xf bound_ctrl:1
	v_mov_b32_dpp v218, v36 quad_perm:[1,0,3,2] row_mask:0xf bank_mask:0xf bound_ctrl:1
	v_mov_b32_dpp v219, v38 quad_perm:[1,0,3,2] row_mask:0xf bank_mask:0xf bound_ctrl:1
	v_mov_b32_dpp v220, v40 quad_perm:[1,0,3,2] row_mask:0xf bank_mask:0xf bound_ctrl:1
	v_mov_b32_dpp v221, v42 quad_perm:[1,0,3,2] row_mask:0xf bank_mask:0xf bound_ctrl:1
	v_mov_b32_dpp v222, v44 quad_perm:[1,0,3,2] row_mask:0xf bank_mask:0xf bound_ctrl:1
	v_mov_b32_dpp v223, v45 quad_perm:[1,0,3,2] row_mask:0xf bank_mask:0xf bound_ctrl:1
	v_mov_b32_dpp v224, v43 quad_perm:[1,0,3,2] row_mask:0xf bank_mask:0xf bound_ctrl:1
	v_mov_b32_dpp v225, v41 quad_perm:[1,0,3,2] row_mask:0xf bank_mask:0xf bound_ctrl:1
	v_mov_b32_dpp v226, v39 quad_perm:[1,0,3,2] row_mask:0xf bank_mask:0xf bound_ctrl:1
	v_mov_b32_dpp v227, v37 quad_perm:[1,0,3,2] row_mask:0xf bank_mask:0xf bound_ctrl:1
	v_mov_b32_dpp v228, v35 quad_perm:[1,0,3,2] row_mask:0xf bank_mask:0xf bound_ctrl:1
	v_mov_b32_dpp v229, v33 quad_perm:[1,0,3,2] row_mask:0xf bank_mask:0xf bound_ctrl:1
	v_mov_b32_dpp v230, v19 quad_perm:[1,0,3,2] row_mask:0xf bank_mask:0xf bound_ctrl:1
	v_mov_b32_dpp v231, v18 quad_perm:[1,0,3,2] row_mask:0xf bank_mask:0xf bound_ctrl:1
	v_mov_b32_dpp v232, v17 quad_perm:[1,0,3,2] row_mask:0xf bank_mask:0xf bound_ctrl:1
	v_mov_b32_dpp v233, v16 quad_perm:[1,0,3,2] row_mask:0xf bank_mask:0xf bound_ctrl:1
	v_mov_b32_dpp v234, v15 quad_perm:[1,0,3,2] row_mask:0xf bank_mask:0xf bound_ctrl:1
	v_mov_b32_dpp v235, v14 quad_perm:[1,0,3,2] row_mask:0xf bank_mask:0xf bound_ctrl:1
	v_mov_b32_dpp v236, v13 quad_perm:[1,0,3,2] row_mask:0xf bank_mask:0xf bound_ctrl:1
	v_mov_b32_dpp v237, v12 quad_perm:[1,0,3,2] row_mask:0xf bank_mask:0xf bound_ctrl:1
	v_mov_b32_dpp v238, v9 quad_perm:[1,0,3,2] row_mask:0xf bank_mask:0xf bound_ctrl:1
	v_mov_b32_dpp v239, v8 quad_perm:[1,0,3,2] row_mask:0xf bank_mask:0xf bound_ctrl:1
	s_waitcnt vmcnt(0)
; DI unsigned pack2(float lo, float hi) { const f32x2 v = (f32x2){lo, hi}; return __builtin_bit_cast(unsigned, __builtin_convertvector(v, bf16x2_t)); }
; template <int CTRL> DI float dpp_f(float x) { return __int_as_float(__builtin_amdgcn_update_dpp(0, __float_as_int(x), CTRL, 0xF, 0xF, true)); }
; template <int HS>
; DI void qknorm_phase(bf16_t* QK, int RL, const float* kgain, int gain_mod, const f32x2* rope) {
;     ...
;         for (int e = 0; e < HS; ++e) {
;             float v = x[e] * r * gn[e];
;             const float o = dpp_f<0xB1>(v);
;             if (lat) { const f32x2 cs = rp[e]; v = half ? (o * cs[1] + v * cs[0]) : (v * cs[0] - o * cs[1]); }
;             x[e] = v;
;         }
;         if (act) {
; #pragma unroll
;             for (int c = 0; c < HS / 8; ++c) { u32x4 w; w.x = pack2(x[c * 8], x[c * 8 + 1]); w.y = pack2(x[c * 8 + 2], x[c * 8 + 3]); w.z = pack2(x[c * 8 + 4], x[c * 8 + 5]); w.w = pack2(x[c * 8 + 6], x[c * 8 + 7]);
;                 *(u32x4*)(ptr + c * 8) = w; }
;         }
	v_mul_f32_e32 v208, v145, v208
	v_mul_f32_e32 v209, v147, v209
	v_mul_f32_e32 v210, v149, v210
	v_mul_f32_e32 v211, v151, v211
	v_mul_f32_e32 v212, v153, v212
	v_mul_f32_e32 v213, v155, v213
	v_mul_f32_e32 v214, v157, v214
	v_mul_f32_e32 v215, v159, v215
	v_mul_f32_e32 v216, v161, v216
	v_mul_f32_e32 v217, v163, v217
	v_mul_f32_e32 v218, v165, v218
	v_mul_f32_e32 v219, v167, v219
	v_mul_f32_e32 v220, v169, v220
	v_mul_f32_e32 v221, v171, v221
	v_mul_f32_e32 v222, v173, v222
	v_mul_f32_e32 v223, v175, v223
	v_mul_f32_e32 v224, v177, v224
	v_mul_f32_e32 v225, v179, v225
	v_mul_f32_e32 v226, v181, v226
	v_mul_f32_e32 v227, v183, v227
	v_mul_f32_e32 v228, v185, v228
	v_mul_f32_e32 v229, v187, v229
	v_mul_f32_e32 v230, v189, v230
	v_mul_f32_e32 v231, v191, v231
	v_mul_f32_e32 v232, v193, v232
	v_mul_f32_e32 v233, v195, v233
	v_mul_f32_e32 v234, v197, v234
	v_mul_f32_e32 v235, v199, v235
	v_mul_f32_e32 v236, v201, v236
	v_mul_f32_e32 v237, v203, v237
	v_mul_f32_e32 v238, v205, v238
	v_mul_f32_e32 v239, v207, v239
	v_cndmask_b32_e64 v208, v208, -v208, vcc
	v_cndmask_b32_e64 v209, v209, -v209, vcc
	v_cndmask_b32_e64 v210, v210, -v210, vcc
	v_cndmask_b32_e64 v211, v211, -v211, vcc
	v_cndmask_b32_e64 v212, v212, -v212, vcc
	v_cndmask_b32_e64 v213, v213, -v213, vcc
	v_cndmask_b32_e64 v214, v214, -v214, vcc
	v_cndmask_b32_e64 v215, v215, -v215, vcc
	v_cndmask_b32_e64 v216, v216, -v216, vcc
	v_cndmask_b32_e64 v217, v217, -v217, vcc
	v_cndmask_b32_e64 v218, v218, -v218, vcc
	v_cndmask_b32_e64 v219, v219, -v219, vcc
	v_cndmask_b32_e64 v220, v220, -v220, vcc
	v_cndmask_b32_e64 v221, v221, -v221, vcc
	v_cndmask_b32_e64 v222, v222, -v222, vcc
	v_cndmask_b32_e64 v223, v223, -v223, vcc
	v_cndmask_b32_e64 v224, v224, -v224, vcc
	v_cndmask_b32_e64 v225, v225, -v225, vcc
	v_cndmask_b32_e64 v226, v226, -v226, vcc
	v_cndmask_b32_e64 v227, v227, -v227, vcc
	v_cndmask_b32_e64 v228, v228, -v228, vcc
	v_cndmask_b32_e64 v229, v229, -v229, vcc
	v_cndmask_b32_e64 v230, v230, -v230, vcc
	v_cndmask_b32_e64 v231, v231, -v231, vcc
	v_cndmask_b32_e64 v232, v232, -v232, vcc
	v_cndmask_b32_e64 v233, v233, -v233, vcc
	v_cndmask_b32_e64 v234, v234, -v234, vcc
	v_cndmask_b32_e64 v235, v235, -v235, vcc
	v_cndmask_b32_e64 v236, v236, -v236, vcc
	v_cndmask_b32_e64 v237, v237, -v237, vcc
	v_cndmask_b32_e64 v238, v238, -v238, vcc
	v_cndmask_b32_e64 v239, v239, -v239, vcc
	v_fmac_f32_e32 v208, v0, v144
	v_fmac_f32_e32 v209, v25, v146
	v_fmac_f32_e32 v210, v26, v148
	v_fmac_f32_e32 v211, v27, v150
	v_fmac_f32_e32 v212, v28, v152
	v_fmac_f32_e32 v213, v29, v154
	v_fmac_f32_e32 v214, v30, v156
	v_fmac_f32_e32 v215, v31, v158
	v_fmac_f32_e32 v216, v32, v160
	v_fmac_f32_e32 v217, v34, v162
	v_fmac_f32_e32 v218, v36, v164
	v_fmac_f32_e32 v219, v38, v166
	v_fmac_f32_e32 v220, v40, v168
	v_fmac_f32_e32 v221, v42, v170
	v_fmac_f32_e32 v222, v44, v172
	v_fmac_f32_e32 v223, v45, v174
	v_fmac_f32_e32 v224, v43, v176
	v_fmac_f32_e32 v225, v41, v178
	v_fmac_f32_e32 v226, v39, v180
	v_fmac_f32_e32 v227, v37, v182
	v_fmac_f32_e32 v228, v35, v184
	v_fmac_f32_e32 v229, v33, v186
	v_fmac_f32_e32 v230, v19, v188
	v_fmac_f32_e32 v231, v18, v190
	v_fmac_f32_e32 v232, v17, v192
	v_fmac_f32_e32 v233, v16, v194
	v_fmac_f32_e32 v234, v15, v196
	v_fmac_f32_e32 v235, v14, v198
	v_fmac_f32_e32 v236, v13, v200
	v_fmac_f32_e32 v237, v12, v202
	v_fmac_f32_e32 v238, v9, v204
	v_fmac_f32_e32 v239, v8, v206
	v_cndmask_b32_e64 v0, v0, v208, s[0:1]
	v_cndmask_b32_e64 v25, v25, v209, s[0:1]
	v_cndmask_b32_e64 v26, v26, v210, s[0:1]
	v_cndmask_b32_e64 v27, v27, v211, s[0:1]
	v_cndmask_b32_e64 v28, v28, v212, s[0:1]
	v_cndmask_b32_e64 v29, v29, v213, s[0:1]
	v_cndmask_b32_e64 v30, v30, v214, s[0:1]
	v_cndmask_b32_e64 v31, v31, v215, s[0:1]
	v_cndmask_b32_e64 v32, v32, v216, s[0:1]
	v_cndmask_b32_e64 v34, v34, v217, s[0:1]
	v_cndmask_b32_e64 v36, v36, v218, s[0:1]
	v_cndmask_b32_e64 v38, v38, v219, s[0:1]
	v_cndmask_b32_e64 v40, v40, v220, s[0:1]
	v_cndmask_b32_e64 v42, v42, v221, s[0:1]
	v_cndmask_b32_e64 v44, v44, v222, s[0:1]
	v_cndmask_b32_e64 v45, v45, v223, s[0:1]
	v_cndmask_b32_e64 v43, v43, v224, s[0:1]
	v_cndmask_b32_e64 v41, v41, v225, s[0:1]
	v_cndmask_b32_e64 v39, v39, v226, s[0:1]
	v_cndmask_b32_e64 v37, v37, v227, s[0:1]
	v_cndmask_b32_e64 v35, v35, v228, s[0:1]
	v_cndmask_b32_e64 v33, v33, v229, s[0:1]
	v_cndmask_b32_e64 v19, v19, v230, s[0:1]
	v_cndmask_b32_e64 v18, v18, v231, s[0:1]
	v_cndmask_b32_e64 v17, v17, v232, s[0:1]
	v_cndmask_b32_e64 v16, v16, v233, s[0:1]
	v_cndmask_b32_e64 v15, v15, v234, s[0:1]
	v_cndmask_b32_e64 v14, v14, v235, s[0:1]
	v_cndmask_b32_e64 v13, v13, v236, s[0:1]
	v_cndmask_b32_e64 v12, v12, v237, s[0:1]
	v_cndmask_b32_e64 v9, v9, v238, s[0:1]
	v_cndmask_b32_e64 v8, v8, v239, s[0:1]
	s_and_saveexec_b64 s[0:1], s[2:3]
	s_cbranch_execz .LBB0_1164
	v_cvt_pk_bf16_f32 v24, v0, v25
	v_cvt_pk_bf16_f32 v25, v26, v27
	v_cvt_pk_bf16_f32 v26, v28, v29
	v_cvt_pk_bf16_f32 v27, v30, v31
	global_store_dwordx4 v[6:7], v[24:27], off offset:2048
	v_cvt_pk_bf16_f32 v10, v17, v16
	v_cvt_pk_bf16_f32 v11, v15, v14
	v_cvt_pk_bf16_f32 v24, v32, v34
	v_cvt_pk_bf16_f32 v25, v36, v38
	v_cvt_pk_bf16_f32 v26, v40, v42
	v_cvt_pk_bf16_f32 v27, v44, v45
	global_store_dwordx4 v[6:7], v[24:27], off offset:2064
	v_cvt_pk_bf16_f32 v12, v13, v12
	v_cvt_pk_bf16_f32 v13, v9, v8
	v_cvt_pk_bf16_f32 v24, v43, v41
	v_cvt_pk_bf16_f32 v25, v39, v37
	v_cvt_pk_bf16_f32 v26, v35, v33
	v_cvt_pk_bf16_f32 v27, v19, v18
	global_store_dwordx4 v[6:7], v[24:27], off offset:2080
	global_store_dwordx4 v[6:7], v[10:13], off offset:2096
	s_branch .LBB0_1164
